# v15 + tagged-slot row-statistic exchange in the w_o and down epilogues when co-located (no write-through ack wait, counter atomic, single-wave poll, barrier); slots zeroed at entry
# speedup vs baseline: 1.0074x; 1.0022x over previous
; #define LAS __attribute__((address_space(3)))
; __global__ void __launch_bounds__(NWAVES * 64, 2) skel_fwd(Args args) {
;     extern __shared__ __attribute__((aligned(16))) unsigned char lds[];
;     Frame F;
;     F.lds = (LAS unsigned char*)lds;
;     F.MISC = (volatile LAS unsigned*)(F.lds + MISC_OFF);
;     F.tid = threadIdx.x; F.lane = F.tid & 63; F.wave = __builtin_amdgcn_readfirstlane(F.tid >> 6);
;     F.G = gridDim.x; { const int bx = blockIdx.x; F.vcu = (F.G % 8 == 0) ? (bx % 8) * (F.G / 8) + bx / 8 : bx; }
_Z8skel_fwd4Args:
	s_load_dword s93, s[0:1], 0xc8
	s_load_dwordx2 s[88:89], s[0:1], 0xc0
	s_mov_b32 s96, s2
	s_add_u32 s2, s0, 0xc8
	s_addc_u32 s3, s1, 0
	v_readfirstlane_b32 s4, v0
	v_writelane_b32 v241, s2, 0
	s_mov_b32 s84, s96
	s_nop 0
	v_writelane_b32 v241, s3, 1
	s_waitcnt lgkmcnt(0)
	s_lshl_b32 s100, s96, 12
	v_lshl_add_u32 v1, v0, 3, s100
	v_mov_b32_e32 v2, 0
	v_mov_b32_e32 v3, 0
	s_add_u32 s100, s88, 0x2000000
	s_addc_u32 s101, s89, 0
	global_store_dwordx2 v1, v[2:3], s[100:101]
	s_and_b32 s2, s93, 7
	s_cmp_lg_u32 s2, 0
	s_cbranch_scc0 .LBB0_13
	s_movk_i32 s2, 0x80
	v_cmp_gt_u32_e32 vcc, s2, v0
	s_and_saveexec_b64 s[2:3], vcc

;     __device__ __forceinline__ bool run(const f32x4 (&v)[2][2][4][2], const Unit& u, int wr, int wc, int fr, int fq, PG8_LAS unsigned char* lds, int wid, int lane) const {
;     ...
;         const int row = wid * 32 + (lane & 31);
;         if (lane < 32) {
;             const float s = (P[row * 4 + 0] + P[row * 4 + 1]) + (P[row * 4 + 2] + P[row * 4 + 3]);
;             unsigned long long* slot = (unsigned long long*)xbuf + ((size_t)(u.pm * BM + row) * 4 + u.pn);
;             __hip_atomic_store(slot, ((unsigned long long)__float_as_uint(s) << 32), __ATOMIC_RELAXED, __HIP_MEMORY_SCOPE_AGENT);
;         }
;         asm volatile("s_waitcnt vmcnt(0)" ::: "memory");
;         if (lane == 0) __hip_atomic_fetch_add(cnt + 64 * u.pm, 1u, __ATOMIC_RELAXED, __HIP_MEMORY_SCOPE_AGENT);
.LBB0_1201:
	s_or_b64 exec, exec, s[8:9]
	s_add_u32 s16, s88, 0x2080000
	s_addc_u32 s17, s89, 0
	s_lshl_b32 s28, s1, 5
	s_waitcnt lgkmcnt(0)
	s_barrier
	v_and_or_b32 v215, v215, 31, s28
	v_add_u32_e32 v228, s26, v215
	v_cmp_gt_u32_e64 s[8:9], 32, v219
	v_ashrrev_i32_e32 v229, 31, v228
	s_and_saveexec_b64 s[10:11], s[8:9]
	s_cbranch_execz .LBB0_1203
	v_lshl_add_u32 v223, v215, 4, 0
	ds_read_b128 v[230:233], v223
	v_lshlrev_b64 v[234:235], 5, v[228:229]
	s_ashr_i32 s1, s0, 31
	s_waitcnt lgkmcnt(0)
	v_mov_b32_e32 v236, v231
	v_mov_b32_e32 v237, v232
	v_mov_b32_e32 v231, v233
	v_pk_add_f32 v[230:231], v[236:237], v[230:231]
	v_lshl_add_u64 v[232:233], s[16:17], 0, v[234:235]
	v_pk_add_f32 v[230:231], v[230:231], v[230:231] op_sel:[0,1] op_sel_hi:[1,0]
	v_lshl_add_u64 v[232:233], s[0:1], 3, v[232:233]
	v_mov_b32_e32 v234, 1
	v_mov_b32_e32 v235, v230
	global_store_dwordx2 v[232:233], v[234:235], off sc1
.LBB0_1203:
	s_or_b64 exec, exec, s[10:11]
	s_bitcmp1_b32 s98, 0
	s_cbranch_scc1 .Lxo6
	s_mov_b32 s100, 0
	v_mov_b32_e32 v223, 0
	s_branch .Lxf6
.Lxo6:
	s_waitcnt vmcnt(0)
	s_add_u32 s1, s88, 0x10000
	s_addc_u32 s15, s89, 0
	v_cmp_eq_u32_e64 s[10:11], 0, v219
	s_and_saveexec_b64 s[18:19], s[10:11]
	s_cbranch_execz .LBB0_1206
	s_mov_b64 s[20:21], exec
	v_mbcnt_lo_u32_b32 v223, s20, 0
	v_mbcnt_hi_u32_b32 v223, s21, v223
	v_cmp_eq_u32_e32 vcc, 0, v223
	s_and_b64 s[22:23], exec, vcc
	s_mov_b64 exec, s[22:23]
	s_cbranch_execz .LBB0_1206
	s_lshl_b32 s22, s14, 6
	s_ashr_i32 s23, s22, 31
	s_lshl_b64 s[22:23], s[22:23], 2
	s_add_u32 s22, s1, s22
	s_addc_u32 s23, s15, s23
	s_bcnt1_i32_b64 s20, s[20:21]
	v_mov_b32_e32 v223, 0
	v_mov_b32_e32 v225, s20
	global_atomic_add v223, v225, s[22:23]

;     __device__ __forceinline__ bool run(const f32x4 (&v)[2][2][4][2], const Unit& u, int wr, int wc, int fr, int fq, PG8_LAS unsigned char* lds, int wid, int lane) const {
;     ...
;         const bool bad = flag[0] != 0u;
;         if (lane < 32) {
;             const unsigned long long* slot = (const unsigned long long*)xbuf + (size_t)(u.pm * BM + row) * 4; float q = 0.f;
; #pragma unroll
;             for (int t = 0; t < 4; ++t) if (t < ntn) { const unsigned long long w = __hip_atomic_load(slot + t, __ATOMIC_RELAXED, __HIP_MEMORY_SCOPE_AGENT); q += __uint_as_float((unsigned)(w >> 32)); }
;             float er = eps;
;             if (ssq4) { const f32x4 s4 = *(const f32x4*)(ssq4 + (size_t)(u.pm * BM + row) * 4); const float ms = ((s4[0] + s4[1]) + (s4[2] + s4[3])) * (1.0f / 1024.0f) + eps; er = eps * ms * ms; }
;             S[row] = 1.0f / sqrtf(q / (256.0f * (float)ntn) + er);
.Lxf6:
	s_and_saveexec_b64 s[14:15], s[8:9]
	s_cbranch_execz .LBB0_1223
	v_lshlrev_b64 v[228:229], 5, v[228:229]
	v_lshl_add_u64 v[228:229], s[16:17], 0, v[228:229]
.Lxp6:
	global_load_dwordx2 v[230:231], v[228:229], off sc1
	global_load_dwordx2 v[232:233], v[228:229], off offset:8 sc1
	global_load_dwordx2 v[234:235], v[228:229], off offset:16 sc1
	global_load_dwordx2 v[236:237], v[228:229], off offset:24 sc1
	s_bitcmp1_b32 s98, 0
	s_cbranch_scc1 .Lxk6
	s_waitcnt vmcnt(0)
	v_and_b32_e32 v225, v230, v232
	v_and_b32_e32 v225, v225, v234
	v_and_b32_e32 v225, v225, v236
	v_cmp_ne_u32_e32 vcc, 1, v225
	s_cbranch_vccz .Lxk6
	s_sleep 1
	s_add_i32 s100, s100, 1
	s_cmp_lt_u32 s100, 0x40000
	s_cbranch_scc1 .Lxp6
.Lxk6:
	v_mov_b32_e32 v225, 0x358637bd
	s_mov_b32 s1, 0xf800000
	s_waitcnt vmcnt(0)
	v_mov_b32_e32 v229, v237
	v_mov_b32_e32 v228, 0x260
	v_lshl_add_u32 v215, v215, 2, 0
	s_waitcnt lgkmcnt(1)
	v_add_f32_e32 v227, 0, v231
	v_add_f32_e32 v227, v227, v233
	v_add_f32_e32 v227, v227, v235
	v_add_f32_e32 v227, v227, v229
	v_fmac_f32_e32 v225, 0x3a800000, v227
	v_mul_f32_e32 v227, 0x4f800000, v225
	v_cmp_gt_f32_e32 vcc, s1, v225
	s_nop 1
	v_cndmask_b32_e32 v225, v225, v227, vcc
	v_sqrt_f32_e32 v227, v225
	s_nop 0
	v_add_u32_e32 v229, -1, v227
	v_add_u32_e32 v230, 1, v227
	v_fma_f32 v231, -v229, v227, v225
	v_fma_f32 v232, -v230, v227, v225
	v_cmp_ge_f32_e64 s[10:11], 0, v231
	s_nop 1
	v_cndmask_b32_e64 v227, v227, v229, s[10:11]
	v_cmp_lt_f32_e64 s[10:11], 0, v232
	s_nop 1
	v_cndmask_b32_e64 v227, v227, v230, s[10:11]
	v_mul_f32_e32 v229, 0x37800000, v227
	v_cndmask_b32_e32 v227, v227, v229, vcc
	v_cmp_class_f32_e32 vcc, v225, v228
	s_nop 1
	v_cndmask_b32_e32 v225, v227, v225, vcc
	v_div_scale_f32 v227, s[10:11], v225, v225, 1.0
	v_rcp_f32_e32 v228, v227
	v_div_scale_f32 v229, vcc, 1.0, v225, 1.0
	v_fma_f32 v230, -v227, v228, 1.0
	v_fmac_f32_e32 v228, v230, v228
	v_mul_f32_e32 v230, v229, v228
	v_fma_f32 v231, -v227, v230, v229
	v_fmac_f32_e32 v230, v231, v228
	v_fma_f32 v227, -v227, v230, v229
	v_div_fmas_f32 v227, v227, v228, v230
	v_div_fixup_f32 v225, v227, v225, 1.0
	ds_write_b32 v215, v225 offset:8192

;     __device__ __forceinline__ bool run(const f32x4 (&v)[2][2][4][2], const Unit& u, int wr, int wc, int fr, int fq, PG8_LAS unsigned char* lds, int wid, int lane) const {
;     ...
;         const int row = wid * 32 + (lane & 31);
;         if (lane < 32) {
;             const float s = (P[row * 4 + 0] + P[row * 4 + 1]) + (P[row * 4 + 2] + P[row * 4 + 3]);
;             unsigned long long* slot = (unsigned long long*)xbuf + ((size_t)(u.pm * BM + row) * 4 + u.pn);
;             __hip_atomic_store(slot, ((unsigned long long)__float_as_uint(s) << 32), __ATOMIC_RELAXED, __HIP_MEMORY_SCOPE_AGENT);
;         }
;         asm volatile("s_waitcnt vmcnt(0)" ::: "memory");
;         if (lane == 0) __hip_atomic_fetch_add(cnt + 64 * u.pm, 1u, __ATOMIC_RELAXED, __HIP_MEMORY_SCOPE_AGENT);
.LBB0_1450:
	s_or_b64 exec, exec, s[0:1]
	v_and_b32_e32 v0, 31, v0
	s_waitcnt lgkmcnt(0)
	s_barrier
	s_waitcnt lgkmcnt(0)
	v_lshl_or_b32 v217, s7, 5, v0
	s_add_u32 s8, s88, 0x2000000
	v_add_u32_e32 v0, s16, v217
	s_addc_u32 s9, s89, 0
	v_cmp_gt_u32_e64 s[0:1], 32, v212
	v_ashrrev_i32_e32 v1, 31, v0
	s_and_saveexec_b64 s[2:3], s[0:1]
	s_cbranch_execz .LBB0_1452
	v_lshl_add_u32 v213, v217, 4, 0
	ds_read_b128 v[218:221], v213
	v_lshlrev_b64 v[222:223], 5, v[0:1]
	s_ashr_i32 s7, s6, 31
	s_waitcnt lgkmcnt(0)
	v_mov_b32_e32 v224, v219
	v_mov_b32_e32 v225, v220
	v_mov_b32_e32 v219, v221
	v_pk_add_f32 v[218:219], v[224:225], v[218:219]
	v_lshl_add_u64 v[220:221], s[8:9], 0, v[222:223]
	v_pk_add_f32 v[218:219], v[218:219], v[218:219] op_sel:[0,1] op_sel_hi:[1,0]
	v_lshl_add_u64 v[220:221], s[6:7], 3, v[220:221]
	v_mov_b32_e32 v222, 1
	v_mov_b32_e32 v223, v218
	global_store_dwordx2 v[220:221], v[222:223], off sc1
.LBB0_1452:
	s_or_b64 exec, exec, s[2:3]
	s_bitcmp1_b32 s98, 0
	s_cbranch_scc1 .Lxo8
	s_mov_b32 s100, 0
	v_mov_b32_e32 v212, 0
	s_branch .Lxf8
.Lxo8:
	s_waitcnt vmcnt(0)
	s_add_u32 s5, s88, 0x20000
	s_addc_u32 s12, s89, 0
	v_cmp_eq_u32_e64 s[2:3], 0, v212
	s_and_saveexec_b64 s[6:7], s[2:3]
	s_cbranch_execz .LBB0_1455
	s_mov_b64 s[10:11], exec
	v_mbcnt_lo_u32_b32 v212, s10, 0
	v_mbcnt_hi_u32_b32 v212, s11, v212
	v_cmp_eq_u32_e32 vcc, 0, v212
	s_and_b64 s[14:15], exec, vcc
	s_mov_b64 exec, s[14:15]
	s_cbranch_execz .LBB0_1455
	s_lshl_b32 s14, s4, 6
	s_ashr_i32 s15, s14, 31
	s_lshl_b64 s[14:15], s[14:15], 2
	s_add_u32 s14, s5, s14
	s_addc_u32 s15, s12, s15
	s_bcnt1_i32_b64 s10, s[10:11]
	v_mov_b32_e32 v212, 0
	v_mov_b32_e32 v213, s10
	global_atomic_add v212, v213, s[14:15]

;     __device__ __forceinline__ bool run(const f32x4 (&v)[2][2][4][2], const Unit& u, int wr, int wc, int fr, int fq, PG8_LAS unsigned char* lds, int wid, int lane) const {
;     ...
;         const bool bad = flag[0] != 0u;
;         if (lane < 32) {
;             const unsigned long long* slot = (const unsigned long long*)xbuf + (size_t)(u.pm * BM + row) * 4; float q = 0.f;
; #pragma unroll
;             for (int t = 0; t < 4; ++t) if (t < ntn) { const unsigned long long w = __hip_atomic_load(slot + t, __ATOMIC_RELAXED, __HIP_MEMORY_SCOPE_AGENT); q += __uint_as_float((unsigned)(w >> 32)); }
;             float er = eps;
;             if (ssq4) { const f32x4 s4 = *(const f32x4*)(ssq4 + (size_t)(u.pm * BM + row) * 4); const float ms = ((s4[0] + s4[1]) + (s4[2] + s4[3])) * (1.0f / 1024.0f) + eps; er = eps * ms * ms; }
;             S[row] = 1.0f / sqrtf(q / (256.0f * (float)ntn) + er);
.Lxf8:
	s_and_saveexec_b64 s[2:3], s[0:1]
	s_cbranch_execz .LBB0_1472
	v_lshlrev_b64 v[218:219], 5, v[0:1]
	v_lshl_add_u64 v[0:1], v[0:1], 4, s[88:89]
	v_add_co_u32_e32 v0, vcc, 0x2100000, v0
	v_lshl_add_u64 v[218:219], s[8:9], 0, v[218:219]
	s_nop 0
	v_addc_co_u32_e32 v1, vcc, 0, v1, vcc
.Lxp8:
	global_load_dwordx2 v[222:223], v[218:219], off sc1
	global_load_dwordx2 v[224:225], v[218:219], off offset:8 sc1
	global_load_dwordx2 v[226:227], v[218:219], off offset:16 sc1
	global_load_dwordx2 v[228:229], v[218:219], off offset:24 sc1
	s_bitcmp1_b32 s98, 0
	s_cbranch_scc1 .Lxk8
	s_waitcnt vmcnt(0)
	v_and_b32_e32 v213, v222, v224
	v_and_b32_e32 v213, v213, v226
	v_and_b32_e32 v213, v213, v228
	v_cmp_ne_u32_e32 vcc, 1, v213
	s_cbranch_vccz .Lxk8
	s_sleep 1
	s_add_i32 s100, s100, 1
	s_cmp_lt_u32 s100, 0x40000
	s_cbranch_scc1 .Lxp8
.Lxk8:
	v_mov_b32_e32 v213, 0x358637bd
	global_load_dwordx4 v[218:221], v[0:1], off
	s_mov_b32 s0, 0xf800000
	s_waitcnt vmcnt(0)
	v_add_f32_e32 v0, 0, v223
	v_add_f32_e32 v222, v0, v225
	v_mov_b32_e32 v0, v219
	v_mov_b32_e32 v1, v220
	v_mov_b32_e32 v219, v221
	v_pk_add_f32 v[0:1], v[0:1], v[218:219]
	v_add_f32_e32 v220, v222, v227
	v_add_f32_e32 v0, v0, v1
	v_fmac_f32_e32 v213, 0x3a800000, v0
	v_mul_f32_e32 v0, 0x358637bd, v213
	v_add_f32_e32 v218, v220, v229
	v_mul_f32_e32 v0, v213, v0
	v_fmac_f32_e32 v0, 0x3a800000, v218
	v_mul_f32_e32 v1, 0x4f800000, v0
	v_cmp_gt_f32_e32 vcc, s0, v0
	v_mov_b32_e32 v213, 0x260
	s_nop 0
	v_cndmask_b32_e32 v0, v0, v1, vcc
	v_sqrt_f32_e32 v1, v0
	s_nop 0
	v_add_u32_e32 v218, -1, v1
	v_add_u32_e32 v219, 1, v1
	v_fma_f32 v220, -v218, v1, v0
	v_fma_f32 v221, -v219, v1, v0
	v_cmp_ge_f32_e64 s[0:1], 0, v220
	s_nop 1
	v_cndmask_b32_e64 v1, v1, v218, s[0:1]
	v_cmp_lt_f32_e64 s[0:1], 0, v221
	s_nop 1
	v_cndmask_b32_e64 v1, v1, v219, s[0:1]
	v_mul_f32_e32 v218, 0x37800000, v1
	v_cndmask_b32_e32 v1, v1, v218, vcc
	v_cmp_class_f32_e32 vcc, v0, v213
	s_nop 1
	v_cndmask_b32_e32 v0, v1, v0, vcc
	v_div_scale_f32 v1, s[0:1], v0, v0, 1.0
	v_rcp_f32_e32 v213, v1
	v_div_scale_f32 v218, vcc, 1.0, v0, 1.0
	v_fma_f32 v219, -v1, v213, 1.0
	v_fmac_f32_e32 v213, v219, v213
	v_mul_f32_e32 v219, v218, v213
	v_fma_f32 v220, -v1, v219, v218
	v_fmac_f32_e32 v219, v220, v213
	v_fma_f32 v1, -v1, v219, v218
	v_div_fmas_f32 v1, v1, v213, v219
	v_div_fixup_f32 v0, v1, v0, 1.0
	v_lshl_add_u32 v1, v217, 2, 0
	ds_write_b32 v1, v0 offset:8192
